# v132 + differential-attention units handed out dynamically (ticket counter, longest units first, LDS mailbox); phase order unchanged
# baseline (speedup 1.0000x reference)
.LBB0_548:
	s_or_b64 exec, exec, s[4:5]
	s_cmpk_gt_i32 s3, 0xff
	s_waitcnt lgkmcnt(0)
	s_barrier
	s_cbranch_scc1 .LBB0_582
	v_mov_b32_e32 v213, 0
	global_load_dword v227, v213, s[52:53]
	v_mbcnt_lo_u32_b32 v0, -1, 0
	s_mov_b32 s5, 0
	s_movk_i32 s44, 0x3000
	v_mov_b64_e32 v[214:215], s[12:13]
	s_mov_b64 s[6:7], 0x1800
	s_movk_i32 s45, 0x1000
	s_movk_i32 s46, 0x110
	s_movk_i32 s47, 0x2000
	s_movk_i32 s48, 0x90
	s_mov_b32 s49, 0xf149f2ca
	s_mov_b32 s50, 0x41000000
	v_mbcnt_hi_u32_b32 v228, -1, v0
	s_mov_b32 s51, 0x800000
	s_movk_i32 s52, 0x4000
	s_mov_b32 s53, 0x8000
	s_mov_b32 s54, 0xc000
	s_mov_b32 s55, 0x10000
	s_mov_b32 s56, 0x14000
	s_mov_b32 s57, 0x18000
	v_mov_b32_e32 v229, 0xf149f2ca
	s_mov_b32 s58, s3
	s_cmpk_lg_u32 s24, 0x100
	s_cbranch_scc1 .Ldf_noremap
	s_mov_b32 s97, s3
	s_branch .Ldq_unit
	s_and_b32 s58, s3, 7
	s_lshl_b32 s58, s58, 1
	s_lshr_b32 s96, s3, 7
	s_add_i32 s58, s58, s96
	s_lshl_b32 s58, s58, 4
	s_bfe_u32 s96, s3, 0x40003
	s_or_b32 s58, s58, s96

.LBB0_552:
	s_cmpk_lg_u32 s24, 0x100
	s_cbranch_scc1 .Ldq_static
	v_readfirstlane_b32 s96, v225
	v_mov_b32_e32 v236, 0x20400
	s_nop 3
	s_cmp_ge_u32 s96, 64
	s_cbranch_scc1 .Ldq_nw
	v_mov_b32_e32 v237, s98
	ds_write_b32 v236, v237
	s_waitcnt lgkmcnt(0)
.Ldq_nw:
	s_barrier
	ds_read_b32 v237, v236
	s_waitcnt lgkmcnt(0)
	v_readfirstlane_b32 s97, v237
	s_nop 3
	s_addk_i32 s97, 0x100
	s_cmpk_gt_i32 s97, 0x3ff
	s_cbranch_scc1 .LBB0_582
.Ldq_unit:
	s_lshr_b32 s59, s97, 6
	s_sub_i32 s59, 15, s59
	s_mov_b32 s61, s59
	s_bfe_u32 s40, s97, 0x30003
	s_mov_b32 s41, 0
	s_lshl_b64 s[38:39], s[40:41], 11
	s_lshl_b32 s62, s40, 3
	s_add_i32 s62, s62, 64
	s_and_b32 s60, s97, 4
	s_and_b32 s63, s97, 3
	s_branch .LBB0_553

.LBB0_553:
	s_or_b32 s4, s63, s60
	v_mov_b32_e32 v233, v225
	s_bitcmp0_b32 s63, 0
	s_cselect_b32 s70, s59, s61
	v_readfirstlane_b32 s68, v233
	s_bfe_u32 s65, s68, 0x20006
	s_lshl_b32 s71, s70, 7
	s_lshl_b32 s67, s65, 5
	v_and_b32_e32 v231, 31, v233
	s_or_b32 s69, s67, s71
	s_add_i32 s40, s4, s62
	v_or_b32_e32 v212, s69, v231
	s_ashr_i32 s41, s40, 31
	s_ashr_i32 s66, s68, 8
	s_lshl_b64 s[42:43], s[40:41], 19
	v_lshl_add_u64 v[0:1], s[38:39], 0, v[212:213]
	s_add_u32 s72, s14, s42
	v_mad_u64_u32 v[2:3], s[40:41], v0, s44, v[214:215]
	s_addc_u32 s73, s15, s43
	v_mad_i32_i24 v3, v1, s44, v3
	s_lshl_b32 s64, s4, 7
	s_lshl_b32 s4, s4, 8
	s_lshl_b32 s40, s66, 6
	v_bfe_u32 v4, v233, 5, 1
	v_lshl_add_u64 v[0:1], v[2:3], 0, s[4:5]
	s_ashr_i32 s41, s40, 31
	v_lshl_add_u64 v[0:1], s[40:41], 1, v[0:1]
	v_lshlrev_b32_e32 v216, 4, v4
	v_mov_b32_e32 v217, v213
	v_lshl_add_u64 v[0:1], v[0:1], 0, v[216:217]
	v_lshl_add_u64 v[2:3], v[0:1], 0, s[6:7]
	v_add_co_u32_e32 v0, vcc, s45, v0
	s_add_u32 s42, s81, s42
	s_nop 0
	v_addc_co_u32_e32 v1, vcc, 0, v1, vcc
	global_load_dwordx4 v[128:131], v[2:3], off offset:32
	global_load_dwordx4 v[132:135], v[2:3], off offset:64
	global_load_dwordx4 v[136:139], v[0:1], off offset:2048
	global_load_dwordx4 v[140:143], v[2:3], off offset:96
	v_lshlrev_b32_e32 v0, 3, v233
	s_addc_u32 s43, s82, s43
	v_ashrrev_i32_e32 v1, 31, v0
	s_lshl_b32 s41, s70, 1
	v_lshlrev_b64 v[0:1], 1, v[0:1]
	v_mov_b32_e32 v246, v0
	v_add_u32_e32 v245, 0x2000, v0
	s_or_b32 s70, s41, 1
	s_mov_b64 s[88:89], s[72:73]
	v_lshl_add_u64 v[218:219], s[72:73], 0, v[0:1]
	s_lshl_b32 s4, s70, 14
	s_mov_b64 s[90:91], s[42:43]
	v_lshl_add_u64 v[220:221], s[42:43], 0, v[0:1]
	v_lshl_add_u64 v[0:1], v[218:219], 0, s[4:5]
	s_barrier
	v_lshl_add_u64 v[2:3], v[220:221], 0, s[4:5]
	global_load_dwordx4 v[144:147], v[0:1], off
	global_load_dwordx4 v[148:151], v[2:3], off
	v_add_co_u32_e32 v0, vcc, s47, v0
	v_lshlrev_b32_e32 v217, 3, v4
	s_nop 0
	v_addc_co_u32_e32 v1, vcc, 0, v1, vcc
	v_add_co_u32_e32 v2, vcc, s47, v2
	v_mul_u32_u24_e32 v230, 0x110, v231
	s_nop 0
	v_addc_co_u32_e32 v3, vcc, 0, v3, vcc
	global_load_dwordx4 v[152:155], v[0:1], off
	global_load_dwordx4 v[156:159], v[2:3], off
	v_lshrrev_b32_e32 v0, 4, v233
	v_lshlrev_b32_e32 v2, 4, v233
	v_mov_b32_e32 v1, 0x14e60
	v_lshrrev_b32_e32 v3, 3, v233
	v_mul_lo_u32 v5, v0, s46
	v_and_b32_e32 v0, 0x70, v2
	v_and_b32_e32 v6, 0xf0, v2
	v_mad_u64_u32 v[222:223], s[42:43], v3, s48, v[0:1]
	v_add3_u32 v234, 0, v5, v6
	v_add_u32_e32 v0, 0, v222
	v_or_b32_e32 v2, s40, v217
	v_lshlrev_b32_e32 v2, 1, v2
	v_mov_b32_e32 v48, v213
	v_mov_b32_e32 v49, v213
	v_mov_b32_e32 v62, v213
	v_mov_b32_e32 v63, v213
	v_lshlrev_b32_e32 v232, 2, v4
	v_add3_u32 v235, 0, v230, v2
	v_mad_u32_u24 v236, v231, s48, v1
	v_mov_b32_e32 v50, v213
	v_mov_b32_e32 v51, v213
	v_mov_b32_e32 v52, v213
	v_mov_b32_e32 v53, v213
	v_mov_b32_e32 v54, v213
	v_mov_b32_e32 v55, v213
	v_mov_b32_e32 v56, v213
	v_mov_b32_e32 v57, v213
	v_mov_b32_e32 v58, v213
	v_mov_b32_e32 v59, v213
	v_mov_b32_e32 v60, v213
	v_mov_b32_e32 v61, v213
	v_mov_b64_e32 v[32:33], v[48:49]
	v_mov_b64_e32 v[16:17], v[48:49]
	s_waitcnt vmcnt(8)
	v_mov_b64_e32 v[78:79], v[62:63]
	s_mov_b32 s72, 1
	s_waitcnt vmcnt(3)
	ds_write_b128 v234, v[144:147]
	s_waitcnt vmcnt(2)
	ds_write_b128 v0, v[148:151] offset:34816
	s_waitcnt vmcnt(1)
	ds_write_b128 v234, v[152:155] offset:8704
	s_waitcnt vmcnt(0)
	ds_write_b128 v0, v[156:159] offset:44032
	v_mov_b32_e32 v0, 0x14e40
	v_mad_u32_u24 v237, v231, s48, v0
	v_mov_b32_e32 v0, 0x14e20
	v_mad_u32_u24 v238, v231, s48, v0
	v_mov_b32_e32 v0, 0x14e00
	v_mad_u32_u24 v239, v231, s48, v0
	v_mov_b32_e32 v0, 0x13c00
	v_mad_u32_u24 v240, v231, s48, v0
	v_mov_b32_e32 v0, 0x12a60
	v_mad_u32_u24 v241, v231, s48, v0
	v_mov_b32_e32 v0, 0x12a40
	v_mad_u32_u24 v242, v231, s48, v0
	v_mov_b32_e32 v0, 0x12a20
	v_mad_u32_u24 v243, v231, s48, v0
	v_mov_b32_e32 v0, 0x12a00
	v_mad_u32_u24 v244, v231, s48, v0
	v_mov_b32_e32 v0, 0x11800
	v_mad_u32_u24 v248, v231, s48, v0
	v_add_u32_e32 v248, v248, v216
	v_mov_b64_e32 v[0:1], v[48:49]
	s_mov_b32 s73, 0
	s_mov_b32 s74, 2
	s_or_b32 s75, s69, 31
	s_mov_b64 s[42:43], 0
	v_mov_b32_e32 v224, 1.0
	v_mov_b32_e32 v249, 0xf149f2ca
	v_mov_b32_e32 v223, 0
	s_mov_b32 s4, s41
	v_mov_b64_e32 v[34:35], v[50:51]
	v_mov_b64_e32 v[36:37], v[52:53]
	v_mov_b64_e32 v[38:39], v[54:55]
	v_mov_b64_e32 v[40:41], v[56:57]
	v_mov_b64_e32 v[42:43], v[58:59]
	v_mov_b64_e32 v[44:45], v[60:61]
	v_mov_b64_e32 v[46:47], v[62:63]
	v_mov_b64_e32 v[18:19], v[50:51]
	v_mov_b64_e32 v[20:21], v[52:53]
	v_mov_b64_e32 v[22:23], v[54:55]
	v_mov_b64_e32 v[24:25], v[56:57]
	v_mov_b64_e32 v[26:27], v[58:59]
	v_mov_b64_e32 v[28:29], v[60:61]
	v_mov_b64_e32 v[30:31], v[62:63]
	v_mov_b64_e32 v[2:3], v[50:51]
	v_mov_b64_e32 v[4:5], v[52:53]
	v_mov_b64_e32 v[6:7], v[54:55]
	v_mov_b64_e32 v[8:9], v[56:57]
	v_mov_b64_e32 v[10:11], v[58:59]
	v_mov_b64_e32 v[12:13], v[60:61]
	v_mov_b64_e32 v[14:15], v[62:63]
	v_mov_b64_e32 v[76:77], v[60:61]
	v_mov_b64_e32 v[74:75], v[58:59]
	v_mov_b64_e32 v[72:73], v[56:57]
	v_mov_b64_e32 v[70:71], v[54:55]
	v_mov_b64_e32 v[68:69], v[52:53]
	v_mov_b64_e32 v[66:67], v[50:51]
	v_mov_b64_e32 v[64:65], v[48:49]
	s_cmpk_lg_u32 s24, 0x100
	s_cbranch_scc1 .Ldq_noat
	s_cmp_ge_u32 s68, 64
	s_cbranch_scc1 .Ldq_noat
	s_add_u32 s94, s22, 0x83600
	s_addc_u32 s95, s23, 0
	s_mov_b64 s[92:93], exec
	s_mov_b64 exec, 1
	v_mov_b32_e32 v237, 0
	v_mov_b32_e32 v238, 1
	global_atomic_add v250, v237, v238, s[94:95] sc0
	s_mov_b64 exec, s[92:93]
.Ldq_noat:
	s_waitcnt lgkmcnt(0)
	s_barrier
	s_branch .LBB0_555

.LBB0_576:
	s_cmpk_lg_u32 s24, 0x100
	s_cbranch_scc1 .Ldq_nocap
	s_cmp_ge_u32 s68, 64
	s_cbranch_scc1 .Ldq_nocap
	s_waitcnt vmcnt(0)
	v_readfirstlane_b32 s98, v250

.LBB0_585:
	s_and_b32 s4, s63, 7
	s_lshl_b32 s5, s4, 2
	v_mov_b32_e32 v6, v225
	s_or_b32 s71, s5, 2
	s_and_b32 s42, s3, 7
	v_readfirstlane_b32 s5, v6
	s_ashr_i32 s64, s5, 6
	s_lshl_b32 s65, s4, 8
	s_ashr_i32 s4, s3, 6
	s_lshl_b32 s5, s42, 8
	s_lshl_b32 s66, s64, 5
	s_add_i32 s66, s66, s5
	s_ashr_i32 s5, s4, 31
	s_bfe_u32 s8, s3, 0x30003
	v_and_b32_e32 v7, 31, v6
	s_lshl_b64 s[38:39], s[4:5], 11
	s_lshl_b32 s4, s4, 3
	s_waitcnt vmcnt(2)
	v_or_b32_e32 v150, s66, v7
	s_or_b32 s4, s4, s8
	s_ashr_i32 s5, s4, 31
	v_ashrrev_i32_e32 v151, 31, v150
	s_lshl_b64 s[4:5], s[4:5], 19
	v_lshl_add_u64 v[2:3], s[38:39], 0, v[150:151]
	s_add_u32 s6, s14, s4
	v_mad_u64_u32 v[4:5], s[40:41], v2, s44, v[146:147]
	v_bfe_u32 v8, v6, 5, 1
	s_addc_u32 s7, s15, s5
	v_mad_i32_i24 v5, v3, s44, v5
	s_lshl_b32 s67, s8, 7
	s_lshl_b32 s8, s8, 8
	v_lshl_add_u64 v[2:3], v[4:5], 0, s[8:9]
	v_lshlrev_b32_e32 v0, 4, v8
	v_lshl_add_u64 v[2:3], v[2:3], 0, v[0:1]
	global_load_dwordx4 v[98:101], v[2:3], off
	global_load_dwordx4 v[102:105], v[2:3], off offset:32
	global_load_dwordx4 v[106:109], v[2:3], off offset:64
	global_load_dwordx4 v[110:113], v[2:3], off offset:96
	global_load_dwordx4 v[114:117], v[2:3], off offset:128
	global_load_dwordx4 v[118:121], v[2:3], off offset:160
	global_load_dwordx4 v[122:125], v[2:3], off offset:192
	global_load_dwordx4 v[126:129], v[2:3], off offset:224
	v_lshlrev_b32_e32 v2, 3, v6
	s_add_u32 s4, s81, s4
	v_ashrrev_i32_e32 v3, 31, v2
	s_addc_u32 s5, s82, s5
	v_lshlrev_b64 v[2:3], 1, v[2:3]
	v_mov_b32_e32 v228, v2
	v_add_u32_e32 v229, 0x2000, v2
	s_waitcnt vmcnt(9)
	s_mov_b64 s[90:91], s[4:5]
	v_lshl_add_u64 v[154:155], s[4:5], 0, v[2:3]
	s_lshl_b32 s4, s42, 16
	s_mov_b64 s[88:89], s[6:7]
	v_lshl_add_u64 v[152:153], s[6:7], 0, v[2:3]
	s_or_b32 s8, s4, 0xc000
	v_lshl_add_u64 v[2:3], v[152:153], 0, s[8:9]
	s_barrier
	v_lshl_add_u64 v[4:5], v[154:155], 0, s[8:9]
	global_load_dwordx4 v[130:133], v[2:3], off
	global_load_dwordx4 v[134:137], v[4:5], off
	v_add_co_u32_e32 v2, vcc, s46, v2
	v_and_b32_e32 v149, 63, v6
	s_nop 0
	v_addc_co_u32_e32 v3, vcc, 0, v3, vcc
	v_add_co_u32_e32 v4, vcc, s46, v4
	v_mul_u32_u24_e32 v197, 0x110, v7
	s_nop 0
	v_addc_co_u32_e32 v5, vcc, 0, v5, vcc
	global_load_dwordx4 v[138:141], v[2:3], off
	global_load_dwordx4 v[142:145], v[4:5], off
	v_lshlrev_b32_e32 v2, 4, v6
	v_lshrrev_b32_e32 v3, 3, v6
	v_lshrrev_b32_e32 v4, 4, v6
	v_and_b32_e32 v148, 0xf0, v2
	v_and_b32_e32 v2, 0x70, v2
	s_waitcnt vmcnt(12)
	v_mad_u64_u32 v[156:157], s[4:5], v4, s47, v[148:149]
	v_mad_u64_u32 v[158:159], s[4:5], v3, s48, v[2:3]
	v_lshlrev_b32_e32 v5, 7, v7
	v_add3_u32 v157, 0, v197, v0
	v_add_u32_e32 v0, 0, v156
	v_add_u32_e32 v2, 0, v158
	v_mov_b32_e32 v14, v1
	v_mov_b32_e32 v15, v1
	v_lshlrev_b32_e32 v151, 3, v8
	s_lshl_b32 s4, s64, 2
	v_lshlrev_b32_e32 v159, 2, v8
	v_sub_u32_e32 v198, v157, v5
	v_mov_b32_e32 v3, v1
	v_mov_b32_e32 v4, v1
	v_mov_b32_e32 v5, v1
	v_mov_b32_e32 v6, v1
	v_mov_b32_e32 v7, v1
	v_mov_b32_e32 v8, v1
	v_mov_b32_e32 v9, v1
	v_mov_b32_e32 v10, v1
	v_mov_b32_e32 v11, v1
	v_mov_b32_e32 v12, v1
	v_mov_b32_e32 v13, v1
	s_add_i32 s69, s4, 0
	v_cmp_eq_u32_e64 s[6:7], 0, v149
	s_or_b32 s68, s66, 30
	s_add_i32 s69, s69, 0x11800
	v_cmp_gt_u32_e64 s[4:5], 32, v149
	s_mov_b64 s[42:43], 0
	s_mov_b32 s70, s9
	s_mov_b32 s8, s71
	s_mov_b32 s71, s9
	s_waitcnt vmcnt(3)
	ds_write_b128 v0, v[130:133]
	s_waitcnt vmcnt(2)
	ds_write_b128 v2, v[134:137] offset:17408
	s_waitcnt vmcnt(1)
	ds_write_b128 v0, v[138:141] offset:8704
	s_waitcnt vmcnt(0)
	ds_write_b128 v2, v[142:145] offset:26624
	v_mov_b32_e32 v0, v1
	v_mov_b32_e32 v2, v1
	v_mov_b64_e32 v[64:65], v[14:15]
	v_mov_b64_e32 v[48:49], v[14:15]
	v_mov_b64_e32 v[32:33], v[14:15]
	v_mov_b64_e32 v[62:63], v[12:13]
	v_mov_b64_e32 v[60:61], v[10:11]
	v_mov_b64_e32 v[58:59], v[8:9]
	v_mov_b64_e32 v[56:57], v[6:7]
	v_mov_b64_e32 v[54:55], v[4:5]
	v_mov_b64_e32 v[52:53], v[2:3]
	v_mov_b64_e32 v[50:51], v[0:1]
	v_mov_b64_e32 v[46:47], v[12:13]
	v_mov_b64_e32 v[44:45], v[10:11]
	v_mov_b64_e32 v[42:43], v[8:9]
	v_mov_b64_e32 v[40:41], v[6:7]
	v_mov_b64_e32 v[38:39], v[4:5]
	v_mov_b64_e32 v[36:37], v[2:3]
	v_mov_b64_e32 v[34:35], v[0:1]
	v_mov_b64_e32 v[30:31], v[12:13]
	v_mov_b64_e32 v[28:29], v[10:11]
	v_mov_b64_e32 v[26:27], v[8:9]
	v_mov_b64_e32 v[24:25], v[6:7]
	v_mov_b64_e32 v[22:23], v[4:5]
	v_mov_b64_e32 v[20:21], v[2:3]
	v_mov_b64_e32 v[18:19], v[0:1]
	v_mov_b64_e32 v[16:17], v[14:15]
	v_mov_b64_e32 v[14:15], v[12:13]
	v_mov_b64_e32 v[12:13], v[10:11]
	v_mov_b64_e32 v[10:11], v[8:9]
	v_mov_b64_e32 v[8:9], v[6:7]
	v_mov_b64_e32 v[6:7], v[4:5]
	v_mov_b64_e32 v[4:5], v[2:3]
	v_mov_b64_e32 v[2:3], v[0:1]
	v_mov_b32_e32 v0, 0
	s_waitcnt lgkmcnt(0)
	s_barrier
	s_branch .LBB0_587
	s_nop 0
	s_nop 0
	s_nop 0
	s_nop 0
	s_nop 0
	s_nop 0
	s_nop 0
	s_nop 0
	s_nop 0
.LBB0_586:
	s_and_b64 vcc, exec, s[40:41]
	s_cbranch_vccnz .LBB0_584

	.amdhsa_kernel _Z14fwd_megakernel4Args
		.amdhsa_group_segment_fixed_size 64
		.amdhsa_private_segment_fixed_size 0
		.amdhsa_kernarg_size 384
		.amdhsa_user_sgpr_count 2
		.amdhsa_user_sgpr_dispatch_ptr 0
		.amdhsa_user_sgpr_queue_ptr 0
		.amdhsa_user_sgpr_kernarg_segment_ptr 1
		.amdhsa_user_sgpr_dispatch_id 0
		.amdhsa_user_sgpr_kernarg_preload_length 0
		.amdhsa_user_sgpr_kernarg_preload_offset 0
		.amdhsa_user_sgpr_private_segment_size 0
		.amdhsa_uses_dynamic_stack 0
		.amdhsa_enable_private_segment 0
		.amdhsa_system_sgpr_workgroup_id_x 1
		.amdhsa_system_sgpr_workgroup_id_y 0
		.amdhsa_system_sgpr_workgroup_id_z 0
		.amdhsa_system_sgpr_workgroup_info 0
		.amdhsa_system_vgpr_workitem_id 2
		.amdhsa_next_free_vgpr 256
		.amdhsa_next_free_sgpr 102
		.amdhsa_accum_offset 256
		.amdhsa_reserve_vcc 1
		.amdhsa_float_round_mode_32 0
		.amdhsa_float_round_mode_16_64 0
		.amdhsa_float_denorm_mode_32 3
		.amdhsa_float_denorm_mode_16_64 3
		.amdhsa_dx10_clamp 1
		.amdhsa_ieee_mode 1
		.amdhsa_fp16_overflow 0
		.amdhsa_tg_split 0
		.amdhsa_exception_fp_ieee_invalid_op 0
		.amdhsa_exception_fp_denorm_src 0
		.amdhsa_exception_fp_ieee_div_zero 0
		.amdhsa_exception_fp_ieee_overflow 0
		.amdhsa_exception_fp_ieee_underflow 0
		.amdhsa_exception_fp_ieee_inexact 0
		.amdhsa_exception_int_div_zero 0
	.end_amdhsa_kernel

amdhsa.kernels:
  - .agpr_count:     0
    .args:
      - .offset:         0
        .size:           128
        .value_kind:     by_value
      - .offset:         128
        .size:           4
        .value_kind:     hidden_block_count_x
      - .offset:         132
        .size:           4
        .value_kind:     hidden_block_count_y
      - .offset:         136
        .size:           4
        .value_kind:     hidden_block_count_z
      - .offset:         140
        .size:           2
        .value_kind:     hidden_group_size_x
      - .offset:         142
        .size:           2
        .value_kind:     hidden_group_size_y
      - .offset:         144
        .size:           2
        .value_kind:     hidden_group_size_z
      - .offset:         146
        .size:           2
        .value_kind:     hidden_remainder_x
      - .offset:         148
        .size:           2
        .value_kind:     hidden_remainder_y
      - .offset:         150
        .size:           2
        .value_kind:     hidden_remainder_z
      - .offset:         168
        .size:           8
        .value_kind:     hidden_global_offset_x
      - .offset:         176
        .size:           8
        .value_kind:     hidden_global_offset_y
      - .offset:         184
        .size:           8
        .value_kind:     hidden_global_offset_z
      - .offset:         192
        .size:           2
        .value_kind:     hidden_grid_dims
      - .offset:         216
        .size:           8
        .value_kind:     hidden_multigrid_sync_arg
      - .offset:         248
        .size:           4
        .value_kind:     hidden_dynamic_lds_size
    .group_segment_fixed_size: 64
    .kernarg_segment_align: 8
    .kernarg_segment_size: 384
    .language:       OpenCL C
    .language_version:
      - 2
      - 0
    .max_flat_workgroup_size: 512
    .name:           _Z14fwd_megakernel4Args
    .private_segment_fixed_size: 0
    .sgpr_count:     108
    .sgpr_spill_count: 0
    .symbol:         _Z14fwd_megakernel4Args.kd
    .uniform_work_group_size: 1
    .uses_dynamic_stack: false
    .vgpr_count:     256
    .vgpr_spill_count: 0
    .wavefront_size: 64
